# pass1 HGRN second load group hoisted on top of gate/convert/GLA-table load batching
# baseline (speedup 1.0000x reference)
; #define LAS __attribute__((address_space(3)))
; __device__ __forceinline__ float sigmoid_(float z) { return __builtin_amdgcn_rcpf(1.f + __expf(-z)); }
; template <int TYPE>
; __device__ __forceinline__ LgRaw lg_issue(const bf16_t* u, int h, int dir, size_t tok0, int tid) {
;     LgRaw r;
;     if constexpr (TYPE == 1) {
;         const int i0 = tid >> 4, d8 = tid & 15, col = (dir ? C_HFB : C_HFF) + h * 128 + d8 * 8;
;         r.a0 = *(const bf16x8*)(u + (tok0 + i0) * DINP + col); r.a1 = *(const bf16x8*)(u + (tok0 + 32 + i0) * DINP + col); r.k = r.a0;
;     } else {
;         const int i = tid >> 3, d8 = tid & 7; const bf16_t* ur = u + (tok0 + i) * DINP;
;         r.a0 = *(const bf16x8*)(ur + (dir ? C_GAB : C_GAF)); r.a1 = *(const bf16x8*)(ur + (dir ? C_GAB : C_GAF) + 8); r.k = *(const bf16x8*)(ur + C_GK + h * 64 + d8 * 8);
;     }
;     return r;
; }
; template <int TYPE>
; __device__ __forceinline__ void lg_compute(const KArgs& a, unsigned char* wsb, int l, int h, int dir, const LgRaw& raw, LAS unsigned char* lds, int tid) {
;     using C = Cfg<TYPE>;
;     LAS float* G = (LAS float*)(lds + SC_G); LAS bf16_t* Kb = (LAS bf16_t*)(lds + SC_K);
;     if constexpr (TYPE == 1) {
;         const float* lbp = (const float*)(wsb + WS_LB) + (dir * DEPTH + l) * 512 + h * 128;
;         const int d8 = tid & 15;
;         const f32x4 lb0 = *(const f32x4*)(lbp + d8 * 8), lb1 = *(const f32x4*)(lbp + d8 * 8 + 4);
;         const float lb[8] = {lb0[0], lb0[1], lb0[2], lb0[3], lb1[0], lb1[1], lb1[2], lb1[3]};
; #pragma unroll
;         for (int e2 = 0; e2 < 2; ++e2) { const int i = (tid >> 4) + 32 * e2;
;             float z[8], lg[8], kk[8]; unpack8(e2 ? raw.a1 : raw.a0, z);
; #pragma unroll
;             for (int e = 0; e < 8; ++e) { const float sg = sigmoid_(fmaxf(z[e], -80.f)); lg[e] = __logf(lb[e] + (1.f - lb[e]) * sg); kk[e] = (1.f - lb[e]) * (1.f - sg); }
.LBB0_265:
	s_ashr_i32 s4, s15, 11
	s_ashr_i32 s5, s4, 31
	s_lshl_b64 s[4:5], s[4:5], 14
	s_and_b32 s6, s14, 0x3fc0
	s_mov_b64 s[12:13], s[68:69]
	s_bfe_i32 s24, s15, 0x10008
	s_bfe_u32 s16, s15, 0x10008
	s_or_b32 s4, s4, s6
	s_add_u32 s6, s12, 0xe300000
	s_addc_u32 s7, s13, 0
	s_lshr_b32 s17, s15, 2
	s_and_b32 s31, s17, 0x180
	v_mov_b32_e32 v12, v195
	s_cmp_eq_u32 s16, 0
	s_cselect_b64 vcc, -1, 0
	v_ashrrev_i32_e32 v8, 4, v12
	s_and_b64 s[18:19], vcc, exec
	s_movk_i32 s17, 0x820
	v_ashrrev_i32_e32 v9, 31, v8
	s_cselect_b32 s34, s17, 0xa20
	v_lshl_add_u64 v[0:1], s[4:5], 0, v[8:9]
	v_mov_b64_e32 v[2:3], s[6:7]
	s_cselect_b32 s30, 1, 14
	s_cselect_b32 s29, 2, 13
	s_cselect_b32 s28, 3, 12
	s_cselect_b32 s27, 4, 11
	s_cselect_b32 s26, 5, 10
	s_cselect_b32 s25, 6, 9
	s_cselect_b32 s23, 9, 6
	s_cselect_b32 s22, 10, 5
	s_cselect_b32 s21, 11, 4
	s_cselect_b32 s20, 12, 3
	s_cselect_b32 s19, 13, 2
	s_cselect_b32 s18, 14, 1
	s_cselect_b32 s17, 15, 0
	s_or_b32 s36, s34, s31
	v_mad_u64_u32 v[2:3], s[34:35], v0, s2, v[2:3]
	s_mulk_i32 s5, 0x2a00
	s_mul_hi_u32 s34, s4, 0x2a00
	s_add_i32 s34, s34, s5
	s_mulk_i32 s4, 0x2a00
	s_add_u32 s4, s6, s4
	s_addc_u32 s5, s7, s34
	s_lshl_b32 s6, s31, 1
	s_add_u32 s4, s4, s6
	s_addc_u32 s5, s5, 0
	v_lshlrev_b32_e32 v13, 3, v12
	s_add_u32 s4, s4, 0x1840
	v_and_b32_e32 v35, 0x78, v13
	s_addc_u32 s5, s5, 0
	v_mad_i32_i24 v3, v1, s2, v3
	v_add_lshl_u32 v112, s36, v35, 1
	v_mov_b64_e32 v[0:1], s[4:5]
	v_lshl_add_u64 v[10:11], v[2:3], 0, v[112:113]
	v_mad_i64_i32 v[2:3], s[4:5], v8, s2, v[0:1]
	v_lshlrev_b32_e32 v112, 1, v35
	v_lshl_add_u64 v[26:27], v[2:3], 0, v[112:113]
	v_add_u32_e32 v2, 32, v8
	v_mad_i64_i32 v[0:1], s[4:5], v2, s2, v[0:1]
	s_lshl_b32 s4, s16, 10
	s_or_b32 s72, s4, s56
	s_lshl_b64 s[4:5], s[72:73], 2
	s_add_u32 s4, s12, s4
	s_addc_u32 s5, s13, s5
	s_lshl_b32 s6, s31, 2
	s_add_u32 s4, s4, s6
	s_addc_u32 s5, s5, 0
	v_lshlrev_b32_e32 v14, 2, v35
	v_mov_b32_e32 v15, v113
	v_lshl_add_u64 v[30:31], v[0:1], 0, v[112:113]
	v_lshl_add_u64 v[0:1], s[4:5], 0, v[14:15]
	s_mov_b64 s[4:5], 0x3e200000
	v_lshl_add_u64 v[2:3], v[0:1], 0, s[4:5]
	s_mov_b32 s4, 0x3e200000
	v_add_co_u32_e64 v0, s[4:5], s4, v0
	s_waitcnt lgkmcnt(0)
	s_nop 0
	v_addc_co_u32_e64 v1, s[4:5], 0, v1, s[4:5]
	s_barrier
	global_load_dwordx4 v[4:7], v[0:1], off
	s_nop 0
	global_load_dwordx4 v[0:3], v[2:3], off offset:16
	v_add_u32_e32 v22, 0, v14
	global_load_dwordx4 v[14:17], v[10:11], off
	s_mov_b32 s37, 0x54000
	v_add_co_u32_e64 v62, s[38:39], s37, v10
	v_sub_u32_e32 v34, v22, v112
	s_movk_i32 s0, 0xff81
	s_nop 1
	v_addc_co_u32_e64 v63, s[38:39], 0, v11, s[38:39]
	global_load_dwordx4 v[64:67], v[62:63], off
	global_load_dwordx4 v[68:71], v[26:27], off
	global_load_dwordx4 v[72:75], v[30:31], off
	s_waitcnt vmcnt(3) lgkmcnt(0)
	v_pk_add_f32 v[36:37], v[4:5], 1.0 op_sel_hi:[1,0] neg_lo:[1,0] neg_hi:[1,0]
	v_pk_add_f32 v[40:41], v[6:7], 1.0 op_sel_hi:[1,0] neg_lo:[1,0] neg_hi:[1,0]
	v_pk_add_f32 v[44:45], v[0:1], 1.0 op_sel_hi:[1,0] neg_lo:[1,0] neg_hi:[1,0]
	v_lshlrev_b32_e32 v9, 16, v14
	v_max_f32_e32 v9, v9, v9
	v_max_f32_e32 v9, 0xc2a00000, v9
	v_mul_f32_e32 v9, 0xbfb8aa3b, v9
	v_exp_f32_e32 v9, v9
	v_and_b32_e32 v14, 0xffff0000, v14
	v_lshlrev_b32_e32 v23, 16, v16
	v_and_b32_e32 v24, 0xffff0000, v16
	v_add_f32_e32 v9, 1.0, v9
	v_rcp_f32_e32 v16, v9
	v_max_f32_e32 v9, v14, v14
	v_max_f32_e32 v9, 0xc2a00000, v9
	v_mul_f32_e32 v9, 0xbfb8aa3b, v9
	v_exp_f32_e32 v9, v9
	v_lshlrev_b32_e32 v28, 16, v17
	v_and_b32_e32 v29, 0xffff0000, v17
	v_lshlrev_b32_e32 v20, 16, v15
	v_add_f32_e32 v9, 1.0, v9
	v_rcp_f32_e32 v17, v9
	v_fma_f32 v9, v36, v16, v4
	v_cmp_gt_f32_e64 s[4:5], s33, v9
	v_and_b32_e32 v21, 0xffff0000, v15
	v_pk_add_f32 v[18:19], v[16:17], 1.0 op_sel_hi:[1,0] neg_lo:[1,0] neg_hi:[1,0]
	v_cndmask_b32_e64 v14, 0, 32, s[4:5]
	v_ldexp_f32 v9, v9, v14
	v_log_f32_e32 v9, v9
	v_pk_mul_f32 v[38:39], v[36:37], v[18:19]
	v_pk_add_f32 v[48:49], v[2:3], 1.0 op_sel_hi:[1,0] neg_lo:[1,0] neg_hi:[1,0]
	v_mul_f32_e32 v14, 0x3f317217, v9
	v_fma_f32 v14, v9, s92, -v14
	v_fmac_f32_e32 v14, 0x3377d1cf, v9
	v_fmac_f32_e32 v14, 0x3f317217, v9
	v_cmp_lt_f32_e64 s[6:7], |v9|, s90
	s_nop 1
	v_cndmask_b32_e64 v9, v9, v14, s[6:7]
	v_cndmask_b32_e64 v14, 0, v238, s[4:5]
	v_sub_f32_e32 v14, v9, v14
	v_fma_f32 v9, v37, v17, v5
	v_cmp_gt_f32_e64 s[4:5], s33, v9
	s_nop 1
	v_cndmask_b32_e64 v15, 0, 32, s[4:5]
	v_ldexp_f32 v9, v9, v15
	v_log_f32_e32 v9, v9
	s_nop 0
	v_mul_f32_e32 v15, 0x3f317217, v9
	v_fma_f32 v15, v9, s92, -v15
	v_fmac_f32_e32 v15, 0x3377d1cf, v9
	v_fmac_f32_e32 v15, 0x3f317217, v9
	v_cmp_lt_f32_e64 s[6:7], |v9|, s90
	s_nop 1
	v_cndmask_b32_e64 v9, v9, v15, s[6:7]
	v_cndmask_b32_e64 v15, 0, v238, s[4:5]
	v_sub_f32_e32 v15, v9, v15
	v_max_f32_e32 v9, v20, v20
	v_max_f32_e32 v9, 0xc2a00000, v9
	v_mul_f32_e32 v9, 0xbfb8aa3b, v9
	v_exp_f32_e32 v9, v9
	s_nop 0
	v_add_f32_e32 v9, 1.0, v9
	v_rcp_f32_e32 v18, v9
	v_max_f32_e32 v9, v21, v21
	v_max_f32_e32 v9, 0xc2a00000, v9
	v_mul_f32_e32 v9, 0xbfb8aa3b, v9
	v_exp_f32_e32 v9, v9
	s_nop 0
	v_add_f32_e32 v9, 1.0, v9
	v_rcp_f32_e32 v19, v9
	v_fma_f32 v9, v40, v18, v6
	v_cmp_gt_f32_e64 s[4:5], s33, v9
	v_pk_add_f32 v[20:21], v[18:19], 1.0 op_sel_hi:[1,0] neg_lo:[1,0] neg_hi:[1,0]
	s_nop 0
	v_cndmask_b32_e64 v16, 0, 32, s[4:5]
	v_ldexp_f32 v9, v9, v16
	v_log_f32_e32 v9, v9
	v_pk_mul_f32 v[42:43], v[40:41], v[20:21]
	v_mul_f32_e32 v16, 0x3f317217, v9
	v_fma_f32 v16, v9, s92, -v16
	v_fmac_f32_e32 v16, 0x3377d1cf, v9
	v_fmac_f32_e32 v16, 0x3f317217, v9
	v_cmp_lt_f32_e64 s[6:7], |v9|, s90
	s_nop 1
	v_cndmask_b32_e64 v9, v9, v16, s[6:7]
	v_cndmask_b32_e64 v16, 0, v238, s[4:5]
	v_sub_f32_e32 v16, v9, v16
	v_fma_f32 v9, v41, v19, v7
; #define LAS __attribute__((address_space(3)))
; __device__ __forceinline__ float sigmoid_(float z) { return __builtin_amdgcn_rcpf(1.f + __expf(-z)); }
; template <int TYPE>
; __device__ __forceinline__ void lg_compute(const KArgs& a, unsigned char* wsb, int l, int h, int dir, const LgRaw& raw, LAS unsigned char* lds, int tid) {
;     ...
;     if constexpr (TYPE == 1) {
;         const float* lbp = (const float*)(wsb + WS_LB) + (dir * DEPTH + l) * 512 + h * 128;
;         const int d8 = tid & 15;
;         const f32x4 lb0 = *(const f32x4*)(lbp + d8 * 8), lb1 = *(const f32x4*)(lbp + d8 * 8 + 4);
;         const float lb[8] = {lb0[0], lb0[1], lb0[2], lb0[3], lb1[0], lb1[1], lb1[2], lb1[3]};
; #pragma unroll
;         for (int e2 = 0; e2 < 2; ++e2) { const int i = (tid >> 4) + 32 * e2;
;             float z[8], lg[8], kk[8]; unpack8(e2 ? raw.a1 : raw.a0, z);
; #pragma unroll
;             for (int e = 0; e < 8; ++e) { const float sg = sigmoid_(fmaxf(z[e], -80.f)); lg[e] = __logf(lb[e] + (1.f - lb[e]) * sg); kk[e] = (1.f - lb[e]) * (1.f - sg); }
;             *(LAS f32x4*)(G + i * C::LDG + d8 * 8) = (f32x4){lg[0], lg[1], lg[2], lg[3]}; *(LAS f32x4*)(G + i * C::LDG + d8 * 8 + 4) = (f32x4){lg[4], lg[5], lg[6], lg[7]};
;             *(LAS bf16x8*)(Kb + i * C::LDK_ + d8 * 8) = pack8(kk); }
	v_cmp_gt_f32_e64 s[4:5], s33, v9
	s_nop 1
	v_cndmask_b32_e64 v17, 0, 32, s[4:5]
	v_ldexp_f32 v9, v9, v17
	v_log_f32_e32 v9, v9
	s_nop 0
	v_mul_f32_e32 v17, 0x3f317217, v9
	v_fma_f32 v17, v9, s92, -v17
	v_fmac_f32_e32 v17, 0x3377d1cf, v9
	v_fmac_f32_e32 v17, 0x3f317217, v9
	v_cmp_lt_f32_e64 s[6:7], |v9|, s90
	s_nop 1
	v_cndmask_b32_e64 v9, v9, v17, s[6:7]
	v_cndmask_b32_e64 v17, 0, v238, s[4:5]
	v_sub_f32_e32 v17, v9, v17
	v_max_f32_e32 v9, v23, v23
	v_max_f32_e32 v9, 0xc2a00000, v9
	v_mul_f32_e32 v9, 0xbfb8aa3b, v9
	v_exp_f32_e32 v9, v9
	s_nop 0
	v_add_f32_e32 v9, 1.0, v9
	v_rcp_f32_e32 v20, v9
	v_max_f32_e32 v9, v24, v24
	v_max_f32_e32 v9, 0xc2a00000, v9
	v_mul_f32_e32 v9, 0xbfb8aa3b, v9
	v_exp_f32_e32 v9, v9
	s_nop 0
	v_add_f32_e32 v9, 1.0, v9
	v_rcp_f32_e32 v21, v9
	v_fma_f32 v9, v44, v20, v0
	v_cmp_gt_f32_e64 s[4:5], s33, v9
	v_pk_add_f32 v[24:25], v[20:21], 1.0 op_sel_hi:[1,0] neg_lo:[1,0] neg_hi:[1,0]
	s_nop 0
	v_cndmask_b32_e64 v18, 0, 32, s[4:5]
	v_ldexp_f32 v9, v9, v18
	v_log_f32_e32 v9, v9
	v_pk_mul_f32 v[46:47], v[44:45], v[24:25]
	v_mul_f32_e32 v18, 0x3f317217, v9
	v_fma_f32 v18, v9, s92, -v18
	v_fmac_f32_e32 v18, 0x3377d1cf, v9
	v_fmac_f32_e32 v18, 0x3f317217, v9
	v_cmp_lt_f32_e64 s[6:7], |v9|, s90
	s_nop 1
	v_cndmask_b32_e64 v9, v9, v18, s[6:7]
	v_cndmask_b32_e64 v18, 0, v238, s[4:5]
	v_sub_f32_e32 v18, v9, v18
	v_fma_f32 v9, v45, v21, v1
	v_cmp_gt_f32_e64 s[4:5], s33, v9
	s_nop 1
	v_cndmask_b32_e64 v19, 0, 32, s[4:5]
	v_ldexp_f32 v9, v9, v19
	v_log_f32_e32 v9, v9
	s_nop 0
	v_mul_f32_e32 v19, 0x3f317217, v9
	v_fma_f32 v19, v9, s92, -v19
	v_fmac_f32_e32 v19, 0x3377d1cf, v9
	v_fmac_f32_e32 v19, 0x3f317217, v9
	v_cmp_lt_f32_e64 s[6:7], |v9|, s90
	s_nop 1
	v_cndmask_b32_e64 v9, v9, v19, s[6:7]
	v_cndmask_b32_e64 v19, 0, v238, s[4:5]
	v_sub_f32_e32 v19, v9, v19
	v_max_f32_e32 v9, v28, v28
	v_max_f32_e32 v9, 0xc2a00000, v9
	v_mul_f32_e32 v9, 0xbfb8aa3b, v9
	v_exp_f32_e32 v9, v9
	s_nop 0
	v_add_f32_e32 v9, 1.0, v9
	v_rcp_f32_e32 v24, v9
	v_max_f32_e32 v9, v29, v29
	v_max_f32_e32 v9, 0xc2a00000, v9
	v_mul_f32_e32 v9, 0xbfb8aa3b, v9
	v_exp_f32_e32 v9, v9
	s_nop 0
	v_add_f32_e32 v9, 1.0, v9
	v_rcp_f32_e32 v25, v9
	v_fma_f32 v9, v48, v24, v2
	v_cmp_gt_f32_e64 s[4:5], s33, v9
	v_pk_add_f32 v[28:29], v[24:25], 1.0 op_sel_hi:[1,0] neg_lo:[1,0] neg_hi:[1,0]
	s_nop 0
	v_cndmask_b32_e64 v20, 0, 32, s[4:5]
	v_ldexp_f32 v9, v9, v20
	v_log_f32_e32 v9, v9
	v_pk_mul_f32 v[50:51], v[48:49], v[28:29]
	v_mul_f32_e32 v20, 0x3f317217, v9
	v_fma_f32 v20, v9, s92, -v20
	v_fmac_f32_e32 v20, 0x3377d1cf, v9
	v_fmac_f32_e32 v20, 0x3f317217, v9
	v_cmp_lt_f32_e64 s[6:7], |v9|, s90
	s_nop 1
	v_cndmask_b32_e64 v9, v9, v20, s[6:7]
	v_cndmask_b32_e64 v20, 0, v238, s[4:5]
	v_sub_f32_e32 v20, v9, v20
	v_fma_f32 v9, v49, v25, v3
	v_cmp_gt_f32_e64 s[4:5], s33, v9
	s_nop 1
	v_cndmask_b32_e64 v21, 0, 32, s[4:5]
	v_ldexp_f32 v9, v9, v21
	v_log_f32_e32 v9, v9
	s_nop 0
	v_mul_f32_e32 v21, 0x3f317217, v9
	v_fma_f32 v21, v9, s92, -v21
	v_fmac_f32_e32 v21, 0x3377d1cf, v9
	v_fmac_f32_e32 v21, 0x3f317217, v9
	v_cmp_lt_f32_e64 s[6:7], |v9|, s90
	s_nop 1
	v_cndmask_b32_e64 v9, v9, v21, s[6:7]
	v_cndmask_b32_e64 v21, 0, v238, s[4:5]
	v_mad_u64_u32 v[52:53], s[4:5], v8, s91, v[22:23]
	v_sub_f32_e32 v21, v9, v21
	s_waitcnt vmcnt(0)
	v_mov_b32_e32 v22, v64
	v_mov_b32_e32 v23, v65
	v_mov_b32_e32 v24, v66
	v_mov_b32_e32 v25, v67
	v_mov_b32_e32 v26, v68
	v_mov_b32_e32 v27, v69
	v_mov_b32_e32 v28, v70
	v_mov_b32_e32 v29, v71
	v_mov_b32_e32 v30, v72
	v_mov_b32_e32 v31, v73
	v_mov_b32_e32 v32, v74
	v_mov_b32_e32 v33, v75
	ds_write_b128 v52, v[14:17]
	ds_write_b128 v52, v[18:21] offset:16
	v_cvt_pk_bf16_f32 v14, v38, v39
	v_cvt_pk_bf16_f32 v15, v42, v43
	v_cvt_pk_bf16_f32 v16, v46, v47
	v_cvt_pk_bf16_f32 v17, v50, v51
	v_mad_u64_u32 v[10:11], s[4:5], v8, s93, v[34:35]
	ds_write_b128 v10, v[14:17] offset:33792
	s_waitcnt vmcnt(0) lgkmcnt(0)
	v_lshlrev_b32_e32 v9, 16, v22
	v_max_f32_e32 v9, v9, v9
	v_max_f32_e32 v9, 0xc2a00000, v9
	v_mul_f32_e32 v9, 0xbfb8aa3b, v9
	v_exp_f32_e32 v9, v9
	v_and_b32_e32 v11, 0xffff0000, v22
	v_lshlrev_b32_e32 v16, 16, v23
	v_and_b32_e32 v17, 0xffff0000, v23
	v_add_f32_e32 v9, 1.0, v9
	v_rcp_f32_e32 v14, v9
	v_lshlrev_b32_e32 v18, 16, v24
	v_and_b32_e32 v19, 0xffff0000, v24
	v_lshlrev_b32_e32 v20, 16, v25
	v_fma_f32 v4, v36, v14, v4
	v_cmp_gt_f32_e64 s[4:5], s33, v4
	v_and_b32_e32 v21, 0xffff0000, v25
	s_nop 0
	v_cndmask_b32_e64 v9, 0, 32, s[4:5]
	v_ldexp_f32 v4, v4, v9
	v_log_f32_e32 v4, v4
	s_nop 0
	v_mul_f32_e32 v9, 0x3f317217, v4
	v_fma_f32 v9, v4, s92, -v9
	v_fmac_f32_e32 v9, 0x3377d1cf, v4
	v_fmac_f32_e32 v9, 0x3f317217, v4
	v_cmp_lt_f32_e64 s[6:7], |v4|, s90
	s_nop 1
	v_cndmask_b32_e64 v4, v4, v9, s[6:7]
	v_cndmask_b32_e64 v9, 0, v238, s[4:5]
	v_sub_f32_e32 v4, v4, v9
	v_max_f32_e32 v9, v11, v11
	v_max_f32_e32 v9, 0xc2a00000, v9
	v_mul_f32_e32 v9, 0xbfb8aa3b, v9
	v_exp_f32_e32 v9, v9
	s_nop 0
	v_add_f32_e32 v9, 1.0, v9
	v_rcp_f32_e32 v15, v9
	s_nop 0
	v_fma_f32 v5, v37, v15, v5
	v_cmp_gt_f32_e64 s[4:5], s33, v5
	v_pk_add_f32 v[14:15], v[14:15], 1.0 op_sel_hi:[1,0] neg_lo:[1,0] neg_hi:[1,0]
	s_nop 0
	v_cndmask_b32_e64 v9, 0, 32, s[4:5]
	v_ldexp_f32 v5, v5, v9
	v_log_f32_e32 v5, v5
	v_pk_mul_f32 v[14:15], v[36:37], v[14:15]
	v_mul_f32_e32 v9, 0x3f317217, v5
	v_fma_f32 v9, v5, s92, -v9
	v_fmac_f32_e32 v9, 0x3377d1cf, v5
	v_fmac_f32_e32 v9, 0x3f317217, v5
	v_cmp_lt_f32_e64 s[6:7], |v5|, s90
	s_nop 1
	v_cndmask_b32_e64 v5, v5, v9, s[6:7]
	v_cndmask_b32_e64 v9, 0, v238, s[4:5]
	v_sub_f32_e32 v5, v5, v9
	v_max_f32_e32 v9, v16, v16
	v_max_f32_e32 v9, 0xc2a00000, v9
	v_mul_f32_e32 v9, 0xbfb8aa3b, v9
	v_exp_f32_e32 v9, v9
	s_nop 0
	v_add_f32_e32 v9, 1.0, v9
; #define LAS __attribute__((address_space(3)))
; __device__ __forceinline__ float sigmoid_(float z) { return __builtin_amdgcn_rcpf(1.f + __expf(-z)); }
; template <int TYPE>
; __device__ __forceinline__ void lg_compute(const KArgs& a, unsigned char* wsb, int l, int h, int dir, const LgRaw& raw, LAS unsigned char* lds, int tid) {
;     ...
;         for (int e2 = 0; e2 < 2; ++e2) { const int i = (tid >> 4) + 32 * e2;
;             float z[8], lg[8], kk[8]; unpack8(e2 ? raw.a1 : raw.a0, z);
; #pragma unroll
;             for (int e = 0; e < 8; ++e) { const float sg = sigmoid_(fmaxf(z[e], -80.f)); lg[e] = __logf(lb[e] + (1.f - lb[e]) * sg); kk[e] = (1.f - lb[e]) * (1.f - sg); }
;             *(LAS f32x4*)(G + i * C::LDG + d8 * 8) = (f32x4){lg[0], lg[1], lg[2], lg[3]}; *(LAS f32x4*)(G + i * C::LDG + d8 * 8 + 4) = (f32x4){lg[4], lg[5], lg[6], lg[7]};
;             *(LAS bf16x8*)(Kb + i * C::LDK_ + d8 * 8) = pack8(kk); }
; __device__ __forceinline__ void vT_write(const VRaw& r, LAS unsigned char* lds, int tid) {
;     LAS bf16_t* VT = (LAS bf16_t*)(lds + SC_VT);
;     const int v8 = tid & 15;
; #pragma unroll
;     for (int e2 = 0; e2 < 2; ++e2) { const int i = (tid >> 4) + 32 * e2; const bf16x8 x = e2 ? r.x1 : r.x0; const int pc = ((((i >> 3) ^ (v8 & 7)) << 3) | (i & 7));
; #pragma unroll
;         for (int e = 0; e < 8; ++e) VT[(v8 * 8 + e) * LDT + pc] = (bf16_t)x[e]; }
; }
	v_rcp_f32_e32 v16, v9
	s_nop 0
	v_fma_f32 v6, v40, v16, v6
	v_cmp_gt_f32_e64 s[4:5], s33, v6
	s_nop 1
	v_cndmask_b32_e64 v9, 0, 32, s[4:5]
	v_ldexp_f32 v6, v6, v9
	v_log_f32_e32 v6, v6
	s_nop 0
	v_mul_f32_e32 v9, 0x3f317217, v6
	v_fma_f32 v9, v6, s92, -v9
	v_fmac_f32_e32 v9, 0x3377d1cf, v6
	v_fmac_f32_e32 v9, 0x3f317217, v6
	v_cmp_lt_f32_e64 s[6:7], |v6|, s90
	s_nop 1
	v_cndmask_b32_e64 v6, v6, v9, s[6:7]
	v_cndmask_b32_e64 v9, 0, v238, s[4:5]
	v_sub_f32_e32 v6, v6, v9
	v_max_f32_e32 v9, v17, v17
	v_max_f32_e32 v9, 0xc2a00000, v9
	v_mul_f32_e32 v9, 0xbfb8aa3b, v9
	v_exp_f32_e32 v9, v9
	s_nop 0
	v_add_f32_e32 v9, 1.0, v9
	v_rcp_f32_e32 v17, v9
	s_nop 0
	v_fmac_f32_e32 v7, v41, v17
	v_cmp_gt_f32_e64 s[4:5], s33, v7
	v_pk_add_f32 v[16:17], v[16:17], 1.0 op_sel_hi:[1,0] neg_lo:[1,0] neg_hi:[1,0]
	s_nop 0
	v_cndmask_b32_e64 v9, 0, 32, s[4:5]
	v_ldexp_f32 v7, v7, v9
	v_log_f32_e32 v7, v7
	v_pk_mul_f32 v[16:17], v[40:41], v[16:17]
	v_mul_f32_e32 v9, 0x3f317217, v7
	v_fma_f32 v9, v7, s92, -v9
	v_fmac_f32_e32 v9, 0x3377d1cf, v7
	v_fmac_f32_e32 v9, 0x3f317217, v7
	v_cmp_lt_f32_e64 s[6:7], |v7|, s90
	s_nop 1
	v_cndmask_b32_e64 v7, v7, v9, s[6:7]
	v_cndmask_b32_e64 v9, 0, v238, s[4:5]
	v_sub_f32_e32 v7, v7, v9
	v_max_f32_e32 v9, v18, v18
	v_max_f32_e32 v9, 0xc2a00000, v9
	v_mul_f32_e32 v9, 0xbfb8aa3b, v9
	v_exp_f32_e32 v9, v9
	s_nop 0
	v_add_f32_e32 v9, 1.0, v9
	v_rcp_f32_e32 v18, v9
	s_nop 0
	v_fma_f32 v0, v44, v18, v0
	v_cmp_gt_f32_e64 s[4:5], s33, v0
	s_nop 1
	v_cndmask_b32_e64 v9, 0, 32, s[4:5]
	v_ldexp_f32 v0, v0, v9
	v_log_f32_e32 v0, v0
	s_nop 0
	v_mul_f32_e32 v9, 0x3f317217, v0
	v_fma_f32 v9, v0, s92, -v9
	v_fmac_f32_e32 v9, 0x3377d1cf, v0
	v_fmac_f32_e32 v9, 0x3f317217, v0
	v_cmp_lt_f32_e64 s[6:7], |v0|, s90
	s_nop 1
	v_cndmask_b32_e64 v0, v0, v9, s[6:7]
	v_cndmask_b32_e64 v9, 0, v238, s[4:5]
	v_sub_f32_e32 v0, v0, v9
	v_max_f32_e32 v9, v19, v19
	v_max_f32_e32 v9, 0xc2a00000, v9
	v_mul_f32_e32 v9, 0xbfb8aa3b, v9
	v_exp_f32_e32 v9, v9
	s_nop 0
	v_add_f32_e32 v9, 1.0, v9
	v_rcp_f32_e32 v19, v9
	s_nop 0
	v_fma_f32 v1, v45, v19, v1
	v_cmp_gt_f32_e64 s[4:5], s33, v1
	v_pk_add_f32 v[18:19], v[18:19], 1.0 op_sel_hi:[1,0] neg_lo:[1,0] neg_hi:[1,0]
	s_nop 0
	v_cndmask_b32_e64 v9, 0, 32, s[4:5]
	v_ldexp_f32 v1, v1, v9
	v_log_f32_e32 v1, v1
	v_pk_mul_f32 v[18:19], v[44:45], v[18:19]
	v_mul_f32_e32 v9, 0x3f317217, v1
	v_fma_f32 v9, v1, s92, -v9
	v_fmac_f32_e32 v9, 0x3377d1cf, v1
	v_fmac_f32_e32 v9, 0x3f317217, v1
	v_cmp_lt_f32_e64 s[6:7], |v1|, s90
	s_nop 1
	v_cndmask_b32_e64 v1, v1, v9, s[6:7]
	v_cndmask_b32_e64 v9, 0, v238, s[4:5]
	v_sub_f32_e32 v1, v1, v9
	v_max_f32_e32 v9, v20, v20
	v_max_f32_e32 v9, 0xc2a00000, v9
	v_mul_f32_e32 v9, 0xbfb8aa3b, v9
	v_exp_f32_e32 v9, v9
	s_nop 0
	v_add_f32_e32 v9, 1.0, v9
	v_rcp_f32_e32 v20, v9
	s_nop 0
	v_fma_f32 v2, v48, v20, v2
	v_cmp_gt_f32_e64 s[4:5], s33, v2
	s_nop 1
	v_cndmask_b32_e64 v9, 0, 32, s[4:5]
	v_ldexp_f32 v2, v2, v9
	v_log_f32_e32 v2, v2
	s_nop 0
	v_mul_f32_e32 v9, 0x3f317217, v2
	v_fma_f32 v9, v2, s92, -v9
	v_fmac_f32_e32 v9, 0x3377d1cf, v2
	v_fmac_f32_e32 v9, 0x3f317217, v2
	v_cmp_lt_f32_e64 s[6:7], |v2|, s90
	s_nop 1
	v_cndmask_b32_e64 v2, v2, v9, s[6:7]
	v_cndmask_b32_e64 v9, 0, v238, s[4:5]
	v_sub_f32_e32 v2, v2, v9
	v_max_f32_e32 v9, v21, v21
	v_max_f32_e32 v9, 0xc2a00000, v9
	v_mul_f32_e32 v9, 0xbfb8aa3b, v9
	v_exp_f32_e32 v9, v9
	s_nop 0
	v_add_f32_e32 v9, 1.0, v9
	v_rcp_f32_e32 v21, v9
	s_nop 0
	v_fmac_f32_e32 v3, v49, v21
	v_cmp_gt_f32_e64 s[4:5], s33, v3
	v_pk_add_f32 v[20:21], v[20:21], 1.0 op_sel_hi:[1,0] neg_lo:[1,0] neg_hi:[1,0]
	s_nop 0
	v_cndmask_b32_e64 v9, 0, 32, s[4:5]
	v_ldexp_f32 v3, v3, v9
	v_log_f32_e32 v3, v3
	v_pk_mul_f32 v[20:21], v[48:49], v[20:21]
	v_mul_f32_e32 v9, 0x3f317217, v3
	v_fma_f32 v9, v3, s92, -v9
	v_fmac_f32_e32 v9, 0x3377d1cf, v3
	v_fmac_f32_e32 v9, 0x3f317217, v3
	v_cmp_lt_f32_e64 s[6:7], |v3|, s90
	s_nop 1
	v_cndmask_b32_e64 v3, v3, v9, s[6:7]
	v_cndmask_b32_e64 v9, 0, v238, s[4:5]
	v_sub_f32_e32 v3, v3, v9
	ds_write_b128 v52, v[4:7] offset:16896
	ds_write_b128 v52, v[0:3] offset:16912
	v_cvt_pk_bf16_f32 v0, v14, v15
	v_cvt_pk_bf16_f32 v1, v16, v17
	v_cvt_pk_bf16_f32 v2, v18, v19
	v_cvt_pk_bf16_f32 v3, v20, v21
	ds_write_b128 v10, v[0:3] offset:42496
	v_and_b32_e32 v0, 56, v13
	v_lshlrev_b32_e32 v1, 1, v8
	v_and_b32_e32 v1, 14, v1
	v_bitop3_b32 v0, v8, v0, -8 bitop3:0x6c
	v_add_u32_e32 v1, s95, v1
	v_lshlrev_b32_e32 v0, 1, v0
	v_mul_u32_u24_e32 v3, 0x90, v35
	v_and_b32_e32 v2, -8, v8
	v_add3_u32 v0, v1, v0, v3
	ds_write_b16 v0, v26
	ds_write_b16_d16_hi v0, v26 offset:144
	ds_write_b16 v0, v27 offset:288
	ds_write_b16_d16_hi v0, v27 offset:432
	ds_write_b16 v0, v28 offset:576
	ds_write_b16_d16_hi v0, v28 offset:720
	ds_write_b16 v0, v29 offset:864
	ds_write_b16_d16_hi v0, v29 offset:1008
	v_add_u32_e32 v0, 32, v2
	v_bitop3_b32 v0, v0, v13, 56 bitop3:0x78
	v_lshlrev_b32_e32 v0, 1, v0
	v_add3_u32 v0, v1, v0, v3
	ds_write_b16 v0, v30
	ds_write_b16_d16_hi v0, v30 offset:144
	ds_write_b16 v0, v31 offset:288
	ds_write_b16_d16_hi v0, v31 offset:432
	ds_write_b16 v0, v32 offset:576
	ds_write_b16_d16_hi v0, v32 offset:720
	ds_write_b16 v0, v33 offset:864
	ds_write_b16_d16_hi v0, v33 offset:1008
	v_ashrrev_i32_e32 v0, 31, v12
	v_lshrrev_b32_e32 v0, 25, v0
	v_add_u32_e32 v0, v12, v0
	v_ashrrev_i32_e32 v1, 7, v0
	v_and_b32_e32 v0, 0x3fffff80, v0
	v_sub_u32_e32 v0, v12, v0
	v_lshlrev_b32_e32 v4, 4, v1
	v_lshlrev_b32_e32 v5, 2, v0
	v_add_u32_e32 v0, 0, v5
	v_and_or_b32 v2, s24, 15, v4
	v_mad_u64_u32 v[2:3], s[4:5], v2, s91, v[0:1]
	s_waitcnt lgkmcnt(0)
	s_barrier
; #define LAS __attribute__((address_space(3)))
; template <int TYPE>
; __device__ __forceinline__ void cumsum_g(int dir, LAS unsigned char* lds, int tid) {
;     using C = Cfg<TYPE>; constexpr int NSEG = 512 / C::DK, SEGL = 64 / NSEG;
;     LAS float* G = (LAS float*)(lds + SC_G); LAS float* SG = (LAS float*)(lds + SC_SEG);
;     const int d = tid % C::DK, seg = tid / C::DK;
;     __syncthreads();
;     float run = 0.f;
; #pragma unroll
;     for (int ii = 0; ii < SEGL; ++ii) { const int i = seg * SEGL + (dir ? SEGL - 1 - ii : ii); run += G[i * C::LDG + d]; G[i * C::LDG + d] = run; }
;     SG[seg * 128 + d] = run;
;     __syncthreads();
;     float off = 0.f;
; #pragma unroll
;     for (int s = 0; s < NSEG; ++s) { const bool before = dir ? (s > seg) : (s < seg); if (before) off += SG[s * 128 + d]; }
	ds_read_b32 v3, v2
	s_waitcnt lgkmcnt(0)
	v_add_f32_e32 v6, 0, v3
	ds_write_b32 v2, v6
	v_or_b32_e32 v2, s30, v4
	v_mad_u64_u32 v[2:3], s[4:5], v2, s91, v[0:1]
	ds_read_b32 v3, v2
	s_waitcnt lgkmcnt(0)
	v_add_f32_e32 v6, v6, v3
	ds_write_b32 v2, v6
	v_or_b32_e32 v2, s29, v4
	v_mad_u64_u32 v[2:3], s[4:5], v2, s91, v[0:1]
	ds_read_b32 v3, v2
	s_waitcnt lgkmcnt(0)
	v_add_f32_e32 v6, v6, v3
	ds_write_b32 v2, v6
	v_or_b32_e32 v2, s28, v4
	v_mad_u64_u32 v[2:3], s[4:5], v2, s91, v[0:1]
	ds_read_b32 v3, v2
	s_waitcnt lgkmcnt(0)
	v_add_f32_e32 v6, v6, v3
	ds_write_b32 v2, v6
	v_or_b32_e32 v2, s27, v4
	v_mad_u64_u32 v[2:3], s[4:5], v2, s91, v[0:1]
	ds_read_b32 v3, v2
	s_waitcnt lgkmcnt(0)
	v_add_f32_e32 v6, v6, v3
	ds_write_b32 v2, v6
	v_or_b32_e32 v2, s26, v4
	v_mad_u64_u32 v[2:3], s[4:5], v2, s91, v[0:1]
	ds_read_b32 v3, v2
	s_waitcnt lgkmcnt(0)
	v_add_f32_e32 v6, v6, v3
	ds_write_b32 v2, v6
	v_or_b32_e32 v2, s25, v4
	v_mad_u64_u32 v[2:3], s[4:5], v2, s91, v[0:1]
	ds_read_b32 v3, v2
	s_add_i32 s4, s16, 7
	s_waitcnt lgkmcnt(0)
	v_add_f32_e32 v6, v6, v3
	ds_write_b32 v2, v6
	v_or_b32_e32 v2, s4, v4
	v_mad_u64_u32 v[2:3], s[4:5], v2, s91, v[0:1]
	ds_read_b32 v3, v2
	s_waitcnt lgkmcnt(0)
	v_add_f32_e32 v6, v6, v3
	ds_write_b32 v2, v6
	v_subrev_u32_e32 v2, s16, v4
	v_mad_u64_u32 v[2:3], s[4:5], v2, s91, v[0:1]
	ds_read_b32 v3, v2 offset:4224
	s_waitcnt lgkmcnt(0)
	v_add_f32_e32 v6, v6, v3
	ds_write_b32 v2, v6 offset:4224
	v_or_b32_e32 v2, s23, v4
	v_mad_u64_u32 v[2:3], s[4:5], v2, s91, v[0:1]
	ds_read_b32 v3, v2
	s_waitcnt lgkmcnt(0)
	v_add_f32_e32 v6, v6, v3
	ds_write_b32 v2, v6
	v_or_b32_e32 v2, s22, v4
	v_mad_u64_u32 v[2:3], s[4:5], v2, s91, v[0:1]
	ds_read_b32 v3, v2
	s_waitcnt lgkmcnt(0)
	v_add_f32_e32 v6, v6, v3
	ds_write_b32 v2, v6
	v_or_b32_e32 v2, s21, v4
	v_mad_u64_u32 v[2:3], s[4:5], v2, s91, v[0:1]
	ds_read_b32 v3, v2
	s_waitcnt lgkmcnt(0)
	v_add_f32_e32 v6, v6, v3
	ds_write_b32 v2, v6
	v_or_b32_e32 v2, s20, v4
	v_mad_u64_u32 v[2:3], s[4:5], v2, s91, v[0:1]
	ds_read_b32 v3, v2
	s_waitcnt lgkmcnt(0)
	v_add_f32_e32 v6, v6, v3
	ds_write_b32 v2, v6
	v_or_b32_e32 v2, s19, v4
	v_mad_u64_u32 v[2:3], s[4:5], v2, s91, v[0:1]
	ds_read_b32 v3, v2
	s_waitcnt lgkmcnt(0)
	v_add_f32_e32 v6, v6, v3
	ds_write_b32 v2, v6
	v_or_b32_e32 v2, s18, v4
	v_mad_u64_u32 v[2:3], s[4:5], v2, s91, v[0:1]
	ds_read_b32 v3, v2
	s_waitcnt lgkmcnt(0)
	v_add_f32_e32 v6, v6, v3
	ds_write_b32 v2, v6
	v_or_b32_e32 v2, s17, v4
	v_mad_u64_u32 v[2:3], s[4:5], v2, s91, v[0:1]
	ds_read_b32 v3, v2
	v_cmp_gt_i32_e64 s[4:5], s0, v12
	s_movk_i32 s0, 0x7f
	v_cmp_lt_i32_e64 s[6:7], s0, v12
	v_cndmask_b32_e64 v4, 0, 1, s[4:5]
	s_waitcnt lgkmcnt(0)
	v_add_f32_e32 v3, v6, v3
	ds_write_b32 v2, v3
	v_lshl_add_u32 v2, v12, 2, s74
	ds_write_b32 v2, v3
	v_cndmask_b32_e64 v3, 0, 1, s[6:7]
	v_cndmask_b32_e32 v3, v4, v3, vcc
	v_and_b32_e32 v3, 1, v3
	v_add_u32_e32 v2, s74, v5
	v_cmp_eq_u32_e64 s[4:5], 1, v3
	v_mov_b32_e32 v3, 0
	s_waitcnt lgkmcnt(0)
	s_barrier
	s_and_saveexec_b64 s[6:7], s[4:5]
	s_cbranch_execz .LBB0_267
	ds_read_b32 v3, v2
	s_waitcnt lgkmcnt(0)
	v_add_f32_e32 v3, 0, v3
